# v31 + SB attention: waves 4-7 (SIMD partners of 0-3) start about 3 us later
# speedup vs baseline: 1.0109x; 1.0109x over previous
; #define LAS __attribute__((address_space(3)))
; __device__ __forceinline__ void sb_attn(const bf16* QKV, bf16* O, LAS unsigned char* lds, int tid) {
;     const int lane = tid & 63, wave = __builtin_amdgcn_readfirstlane(tid >> 6), l32 = lane & 31, hi = lane >> 5;
;     const int vdc = lane & 7, vkg = lane >> 3;
;     LAS unsigned char* vimg = lds + wave * WV_BYTES; LAS unsigned char* kimg = vimg + WV_BUF;
;     const int gw = blockIdx.x * NWAVES + wave, NGW = gridDim.x * NWAVES;
;     for (int u = gw; u < BATCH * 16 * (SEQ / 32); u += NGW) {
;         const int qblk = u & 127, bh = u >> 7, b = bh >> 4, h = bh & 15;
;         const size_t tok0 = (size_t)b * SEQ;
;         const int qr0 = qblk * 32, qpos = qr0 + l32;
;     ...
;             LAS unsigned char* vb = vimg;
; #pragma unroll
;             for (int j = 0; j < 4; ++j) *(LAS bf16x8*)(kimg + (8 * (2 * (j & 1) + (vkg >> 2)) + 4 * (j >> 1) + (vkg & 3)) * WK_ROW + 16 * vdc) = kn[j];
; #pragma unroll
;             for (int j = 0; j < 4; ++j) {
;                 const unsigned w0 = vreg[0][j], w1 = vreg[1][j], w2 = vreg[2][j], w3 = vreg[3][j];
;                 const u32x2 e = {(w0 & 0xffffu) | (w1 << 16), (w2 & 0xffffu) | (w3 << 16)};
;                 const u32x2 o = {(w0 >> 16) | (w1 & 0xffff0000u), (w2 >> 16) | (w3 & 0xffff0000u)};
;                 *(LAS u32x2*)(vb + (8 * vdc + 2 * j) * WV_ROW + 8 * vkg) = e; *(LAS u32x2*)(vb + (8 * vdc + 2 * j + 1) * WV_ROW + 8 * vkg) = o;
.LBB0_189:
	s_and_b64 vcc, exec, s[6:7]
	s_cbranch_vccz .LBB0_200
	v_readfirstlane_b32 s7, v168
	s_ashr_i32 s6, s7, 6
	v_readlane_b32 s8, v253, 8
	s_add_i32 s8, s6, s8
	s_cmpk_gt_i32 s8, 0x3fff
	s_cbranch_scc1 .LBB0_200
	s_and_b32 s14, s6, 4
	s_cmp_eq_u32 s14, 0
	s_cbranch_scc1 .Lsb_nostag
	s_sleep 100
.Lsb_nostag:
	s_waitcnt lgkmcnt(0)
	v_and_b32_e32 v5, 7, v168
	s_mulk_i32 s6, 0x2600
	v_bfe_u32 v3, v168, 5, 1
	v_lshlrev_b32_e32 v156, 4, v5
	s_add_i32 s6, s6, 0
	v_and_b32_e32 v96, 31, v168
	v_bfe_u32 v97, v168, 3, 3
	v_lshlrev_b32_e32 v0, 3, v3
	v_add_u32_e32 v9, s6, v156
	v_mov_b32_e32 v10, s6
	s_movk_i32 s6, 0x90
	v_lshlrev_b32_e32 v113, 4, v3
	v_lshlrev_b32_e32 v4, 2, v3
	v_or_b32_e32 v3, v0, v97
	v_mad_u32_u24 v11, v96, s6, v10
	s_movk_i32 s6, 0x50
	v_and_b32_e32 v1, 63, v168
	v_or_b32_e32 v6, 20, v3
	v_or_b32_e32 v3, 4, v3
	v_and_or_b32 v7, v97, 3, v0
	v_mad_u32_u24 v12, v96, s6, v10
	s_movk_i32 s6, 0x280
	v_readlane_b32 s10, v254, 27
	v_lshlrev_b32_e32 v2, 3, v5
	v_lshlrev_b32_e32 v112, 2, v97
	v_cmp_gt_u32_e64 s[38:39], 32, v1
	s_lshr_b32 s7, s7, 6
	v_and_b32_e32 v1, 32, v168
	v_mul_u32_u24_e32 v6, 0x90, v6
	v_mul_u32_u24_e32 v3, 0x90, v3
	v_mul_u32_u24_e32 v7, 0x90, v7
	v_and_b32_e32 v8, 56, v168
	v_mad_u32_u24 v5, v5, s6, v10
	v_readlane_b32 s11, v254, 28
	v_readlane_b32 s6, v253, 8
	v_lshl_add_u64 v[98:99], s[90:91], 0, v[156:157]
	v_cmp_lt_u32_e64 s[40:41], v113, v96
	v_lshl_add_u64 v[100:101], s[10:11], 0, v[156:157]
	v_or_b32_e32 v114, 0xffffffc0, v112
	s_add_i32 s9, s6, s7
	v_or_b32_e32 v115, 0xffffffc0, v97
	v_lshlrev_b32_e32 v102, 1, v0
	v_lshlrev_b32_e32 v104, 1, v2
	v_lshlrev_b32_e32 v106, 1, v4
	v_add_u32_e32 v116, v9, v7
	v_add_u32_e32 v117, v9, v3
	v_add_u32_e32 v118, v9, v6
	v_add_u32_e32 v119, v5, v8
	v_add_u32_e32 v120, v11, v113
	v_add_u32_e32 v121, v12, v1
	s_branch .LBB0_193
